# LRU chunk summaries stored write-through; split-barrier arrive without L2 writeback or wait
# speedup vs baseline: 1.0115x; 1.0017x over previous
.LBB0_301:
	s_waitcnt lgkmcnt(0)
	s_barrier
	ds_read_b128 v[110:113], v135
	ds_read_b128 v[114:117], v135 offset:4352
	ds_read_b128 v[122:125], v135 offset:8704
	ds_read_b128 v[194:197], v135 offset:13056
	s_waitcnt lgkmcnt(3)
	v_mfma_f32_16x16x32_bf16 v[118:121], v[110:113], v[0:3], 0
	v_mfma_f32_16x16x32_bf16 v[110:113], v[110:113], v[8:11], 0
	ds_read_b128 v[206:209], v135 offset:64
	s_waitcnt lgkmcnt(3)
	v_mfma_f32_16x16x32_bf16 v[198:201], v[114:117], v[0:3], 0
	v_mfma_f32_16x16x32_bf16 v[114:117], v[114:117], v[8:11], 0
	ds_read_b128 v[214:217], v135 offset:4416
	s_waitcnt lgkmcnt(3)
	v_mfma_f32_16x16x32_bf16 v[210:213], v[122:125], v[0:3], 0
	v_mfma_f32_16x16x32_bf16 v[122:125], v[122:125], v[8:11], 0
	ds_read_b128 v[222:225], v135 offset:8768
	s_waitcnt lgkmcnt(3)
	v_mfma_f32_16x16x32_bf16 v[218:221], v[194:197], v[0:3], 0
	v_mfma_f32_16x16x32_bf16 v[194:197], v[194:197], v[8:11], 0
	ds_read_b128 v[226:229], v135 offset:13120
	s_waitcnt lgkmcnt(3)
	v_mfma_f32_16x16x32_bf16 v[118:121], v[206:209], v[4:7], v[118:121]
	v_mfma_f32_16x16x32_bf16 v[110:113], v[206:209], v[12:15], v[110:113]
	ds_read_b128 v[206:209], v135 offset:128
	s_waitcnt lgkmcnt(3)
	v_mfma_f32_16x16x32_bf16 v[198:201], v[214:217], v[4:7], v[198:201]
	v_mfma_f32_16x16x32_bf16 v[114:117], v[214:217], v[12:15], v[114:117]
	ds_read_b128 v[214:217], v135 offset:4480
	s_waitcnt lgkmcnt(3)
	v_mfma_f32_16x16x32_bf16 v[210:213], v[222:225], v[4:7], v[210:213]
	v_mfma_f32_16x16x32_bf16 v[122:125], v[222:225], v[12:15], v[122:125]
	ds_read_b128 v[222:225], v135 offset:8832
	s_waitcnt lgkmcnt(3)
	v_mfma_f32_16x16x32_bf16 v[218:221], v[226:229], v[4:7], v[218:221]
	v_mfma_f32_16x16x32_bf16 v[194:197], v[226:229], v[12:15], v[194:197]
	ds_read_b128 v[226:229], v135 offset:13184
	s_waitcnt lgkmcnt(3)
	v_mfma_f32_16x16x32_bf16 v[118:121], v[206:209], v[16:19], v[118:121]
	v_mfma_f32_16x16x32_bf16 v[110:113], v[206:209], v[28:31], v[110:113]
	ds_read_b128 v[206:209], v135 offset:192
	s_waitcnt lgkmcnt(3)
	v_mfma_f32_16x16x32_bf16 v[198:201], v[214:217], v[16:19], v[198:201]
	v_mfma_f32_16x16x32_bf16 v[114:117], v[214:217], v[28:31], v[114:117]
	ds_read_b128 v[214:217], v135 offset:4544
	s_waitcnt lgkmcnt(3)
	v_mfma_f32_16x16x32_bf16 v[210:213], v[222:225], v[16:19], v[210:213]
	v_mfma_f32_16x16x32_bf16 v[222:225], v[222:225], v[28:31], v[122:125]
	ds_read_b128 v[230:233], v135 offset:8896
	s_waitcnt lgkmcnt(3)
	v_mfma_f32_16x16x32_bf16 v[218:221], v[226:229], v[16:19], v[218:221]
	v_mfma_f32_16x16x32_bf16 v[194:197], v[226:229], v[28:31], v[194:197]
	ds_read_b128 v[234:237], v135 offset:13248
	s_waitcnt lgkmcnt(3)
	v_mfma_f32_16x16x32_bf16 v[226:229], v[206:209], v[20:23], v[118:121]
	v_mfma_f32_16x16x32_bf16 v[206:209], v[206:209], v[32:35], v[110:113]
	s_waitcnt lgkmcnt(2)
	v_mfma_f32_16x16x32_bf16 v[198:201], v[214:217], v[20:23], v[198:201]
	v_mfma_f32_16x16x32_bf16 v[214:217], v[214:217], v[32:35], v[114:117]
	s_waitcnt lgkmcnt(1)
	v_mfma_f32_16x16x32_bf16 v[122:125], v[230:233], v[20:23], v[210:213]
	v_mfma_f32_16x16x32_bf16 v[118:121], v[230:233], v[32:35], v[222:225]
	s_waitcnt lgkmcnt(0)
	v_mfma_f32_16x16x32_bf16 v[114:117], v[234:237], v[20:23], v[218:221]
	v_mfma_f32_16x16x32_bf16 v[110:113], v[234:237], v[32:35], v[194:197]
	s_nop 2
	v_fma_f32 v194, -v226, s4, v90
	v_fma_f32 v195, -v227, s4, v91
	v_pk_fma_f32 v[196:197], v[206:207], s[4:5], v[128:129] op_sel_hi:[1,0,1] neg_lo:[1,0,0] neg_hi:[1,0,0]
	v_exp_f32_e32 v194, v194
	v_exp_f32_e32 v195, v195
	v_exp_f32_e32 v196, v196
	v_exp_f32_e32 v197, v197
	ds_read2st64_b32 v[206:207], v139 offset0:68 offset1:70
	v_pk_add_f32 v[194:195], v[194:195], 1.0 op_sel_hi:[1,0]
	v_pk_fma_f32 v[210:211], v[228:229], s[4:5], v[90:91] op_sel_hi:[1,0,1] neg_lo:[1,0,0] neg_hi:[1,0,0]
	v_rcp_f32_e32 v194, v194
	v_rcp_f32_e32 v195, v195
	v_pk_add_f32 v[196:197], v[196:197], 1.0 op_sel_hi:[1,0]
	v_pk_fma_f32 v[198:199], v[198:199], s[4:5], v[90:91] op_sel_hi:[1,0,1] neg_lo:[1,0,0] neg_hi:[1,0,0]
	v_rcp_f32_e32 v196, v196
	v_pk_mul_f32 v[194:195], v[130:131], v[194:195]
	v_rcp_f32_e32 v197, v197
	v_exp_f32_e32 v194, v194
	v_exp_f32_e32 v195, v195
	v_exp_f32_e32 v198, v198
	v_exp_f32_e32 v199, v199
	v_pk_fma_f32 v[200:201], v[200:201], s[4:5], v[90:91] op_sel_hi:[1,0,1] neg_lo:[1,0,0] neg_hi:[1,0,0]
	v_pk_fma_f32 v[202:203], v[194:195], v[194:195], 1.0 op_sel_hi:[1,1,0] neg_lo:[1,0,0] neg_hi:[1,0,0]
	v_exp_f32_e32 v200, v200
	v_sqrt_f32_e32 v202, v202
	v_sqrt_f32_e32 v203, v203
	v_exp_f32_e32 v201, v201
	v_pk_fma_f32 v[122:123], v[122:123], s[4:5], v[90:91] op_sel_hi:[1,0,1] neg_lo:[1,0,0] neg_hi:[1,0,0]
	v_pk_fma_f32 v[118:119], v[118:119], s[4:5], v[128:129] op_sel_hi:[1,0,1] neg_lo:[1,0,0] neg_hi:[1,0,0]
	v_pk_mul_f32 v[196:197], v[196:197], v[202:203]
	v_exp_f32_e32 v202, v210
	v_exp_f32_e32 v203, v211
	s_waitcnt lgkmcnt(0)
	v_pk_mul_f32 v[196:197], v[206:207], v[196:197]
	ds_write2st64_b32 v139, v194, v195 offset0:196 offset1:198
	ds_write_b32 v141, v197
	v_exp_f32_e32 v122, v122
	v_pk_add_f32 v[194:195], v[202:203], 1.0 op_sel_hi:[1,0]
	v_pk_fma_f32 v[202:203], v[208:209], s[4:5], v[128:129] op_sel_hi:[1,0,1] neg_lo:[1,0,0] neg_hi:[1,0,0]
	v_rcp_f32_e32 v194, v194
	v_rcp_f32_e32 v195, v195
	v_exp_f32_e32 v202, v202
	v_exp_f32_e32 v203, v203
	ds_read2st64_b32 v[208:209], v139 offset0:72 offset1:74
	v_pk_mul_f32 v[194:195], v[130:131], v[194:195]
	v_exp_f32_e32 v123, v123
	v_exp_f32_e32 v194, v194
	v_exp_f32_e32 v195, v195
	v_pk_add_f32 v[202:203], v[202:203], 1.0 op_sel_hi:[1,0]
	v_pk_add_f32 v[122:123], v[122:123], 1.0 op_sel_hi:[1,0]
	v_rcp_f32_e32 v202, v202
	v_pk_fma_f32 v[206:207], v[194:195], v[194:195], 1.0 op_sel_hi:[1,1,0] neg_lo:[1,0,0] neg_hi:[1,0,0]
	v_rcp_f32_e32 v203, v203
	v_sqrt_f32_e32 v206, v206
	v_sqrt_f32_e32 v207, v207
	v_rcp_f32_e32 v122, v122
	v_rcp_f32_e32 v123, v123
	v_exp_f32_e32 v118, v118
	v_pk_mul_f32 v[202:203], v[202:203], v[206:207]
	v_exp_f32_e32 v119, v119
	s_waitcnt lgkmcnt(0)
	v_pk_mul_f32 v[202:203], v[208:209], v[202:203]
	ds_write2st64_b32 v139, v194, v195 offset0:200 offset1:202
	ds_write_b32 v142, v202
	ds_write_b32 v143, v203
	v_pk_add_f32 v[194:195], v[198:199], 1.0 op_sel_hi:[1,0]
	v_pk_fma_f32 v[198:199], v[214:215], s[4:5], v[128:129] op_sel_hi:[1,0,1] neg_lo:[1,0,0] neg_hi:[1,0,0]
	v_rcp_f32_e32 v194, v194
	v_rcp_f32_e32 v195, v195
	v_exp_f32_e32 v198, v198
	v_exp_f32_e32 v199, v199
	ds_read2st64_b32 v[206:207], v139 offset0:100 offset1:102
	v_pk_mul_f32 v[194:195], v[130:131], v[194:195]
	v_pk_mul_f32 v[122:123], v[130:131], v[122:123]
	v_exp_f32_e32 v194, v194
	v_exp_f32_e32 v195, v195
	v_pk_add_f32 v[198:199], v[198:199], 1.0 op_sel_hi:[1,0]
	v_exp_f32_e32 v122, v122
	v_rcp_f32_e32 v198, v198
	v_pk_fma_f32 v[202:203], v[194:195], v[194:195], 1.0 op_sel_hi:[1,1,0] neg_lo:[1,0,0] neg_hi:[1,0,0]
	v_rcp_f32_e32 v199, v199
	v_sqrt_f32_e32 v202, v202
	v_sqrt_f32_e32 v203, v203
	v_exp_f32_e32 v123, v123
	v_pk_add_f32 v[118:119], v[118:119], 1.0 op_sel_hi:[1,0]
	v_pk_fma_f32 v[124:125], v[124:125], s[4:5], v[90:91] op_sel_hi:[1,0,1] neg_lo:[1,0,0] neg_hi:[1,0,0]
	v_pk_mul_f32 v[198:199], v[198:199], v[202:203]
	v_rcp_f32_e32 v118, v118
	s_waitcnt lgkmcnt(0)
	v_pk_mul_f32 v[198:199], v[206:207], v[198:199]
	ds_write2st64_b32 v139, v194, v195 offset0:228 offset1:230
	ds_write_b32 v144, v198
	ds_write_b32 v145, v199
	v_pk_add_f32 v[194:195], v[200:201], 1.0 op_sel_hi:[1,0]
	v_pk_fma_f32 v[198:199], v[216:217], s[4:5], v[128:129] op_sel_hi:[1,0,1] neg_lo:[1,0,0] neg_hi:[1,0,0]
	v_rcp_f32_e32 v194, v194
	v_rcp_f32_e32 v195, v195
	v_exp_f32_e32 v198, v198
	v_exp_f32_e32 v199, v199
	ds_read2st64_b32 v[202:203], v139 offset0:104 offset1:106
	v_pk_mul_f32 v[194:195], v[130:131], v[194:195]
	v_rcp_f32_e32 v119, v119
	v_exp_f32_e32 v194, v194
	v_exp_f32_e32 v195, v195
	v_pk_add_f32 v[198:199], v[198:199], 1.0 op_sel_hi:[1,0]
	v_exp_f32_e32 v124, v124
	v_rcp_f32_e32 v198, v198
	v_pk_fma_f32 v[200:201], v[194:195], v[194:195], 1.0 op_sel_hi:[1,1,0] neg_lo:[1,0,0] neg_hi:[1,0,0]
	v_rcp_f32_e32 v199, v199
	v_sqrt_f32_e32 v200, v200
	v_sqrt_f32_e32 v201, v201
	v_exp_f32_e32 v125, v125
	v_pk_fma_f32 v[114:115], v[114:115], s[4:5], v[90:91] op_sel_hi:[1,0,1] neg_lo:[1,0,0] neg_hi:[1,0,0]
	v_pk_fma_f32 v[120:121], v[120:121], s[4:5], v[128:129] op_sel_hi:[1,0,1] neg_lo:[1,0,0] neg_hi:[1,0,0]
	v_pk_mul_f32 v[198:199], v[198:199], v[200:201]
	v_exp_f32_e32 v114, v114
	s_waitcnt lgkmcnt(0)
	v_pk_mul_f32 v[198:199], v[198:199], v[202:203]
	ds_write2st64_b32 v139, v194, v195 offset0:232 offset1:234
	ds_write_b32 v146, v198
	ds_write_b32 v147, v199
	v_pk_fma_f32 v[194:195], v[122:123], v[122:123], 1.0 op_sel_hi:[1,1,0] neg_lo:[1,0,0] neg_hi:[1,0,0]
	ds_read2st64_b32 v[198:199], v139 offset0:132 offset1:134
	v_sqrt_f32_e32 v194, v194
	v_sqrt_f32_e32 v195, v195
	ds_write_b32 v140, v196
	ds_write_b32 v148, v122
	v_exp_f32_e32 v115, v115
	v_pk_mul_f32 v[118:119], v[118:119], v[194:195]
	v_exp_f32_e32 v120, v120
	s_waitcnt lgkmcnt(2)
	v_pk_mul_f32 v[118:119], v[118:119], v[198:199]
	ds_write_b32 v149, v123
	ds_write_b32 v150, v118
	ds_write_b32 v151, v119
	v_pk_add_f32 v[118:119], v[124:125], 1.0 op_sel_hi:[1,0]
	v_exp_f32_e32 v121, v121
	v_rcp_f32_e32 v118, v118
	v_rcp_f32_e32 v119, v119
	v_pk_add_f32 v[114:115], v[114:115], 1.0 op_sel_hi:[1,0]
	v_pk_add_f32 v[120:121], v[120:121], 1.0 op_sel_hi:[1,0]
	v_rcp_f32_e32 v114, v114
	v_pk_mul_f32 v[118:119], v[130:131], v[118:119]
	v_rcp_f32_e32 v115, v115
	v_exp_f32_e32 v118, v118
	v_exp_f32_e32 v119, v119
	v_rcp_f32_e32 v120, v120
	v_rcp_f32_e32 v121, v121
	ds_read2st64_b32 v[124:125], v139 offset0:136 offset1:138
	v_pk_fma_f32 v[122:123], v[118:119], v[118:119], 1.0 op_sel_hi:[1,1,0] neg_lo:[1,0,0] neg_hi:[1,0,0]
	v_pk_fma_f32 v[110:111], v[110:111], s[4:5], v[128:129] op_sel_hi:[1,0,1] neg_lo:[1,0,0] neg_hi:[1,0,0]
	v_sqrt_f32_e32 v122, v122
	v_sqrt_f32_e32 v123, v123
	v_pk_mul_f32 v[114:115], v[130:131], v[114:115]
	v_exp_f32_e32 v110, v110
	v_exp_f32_e32 v111, v111
	v_exp_f32_e32 v114, v114
	v_exp_f32_e32 v115, v115
	v_pk_mul_f32 v[120:121], v[120:121], v[122:123]
	ds_write_b32 v152, v118
	s_waitcnt lgkmcnt(1)
	v_pk_mul_f32 v[120:121], v[120:121], v[124:125]
	ds_write_b32 v153, v119
	ds_write_b32 v154, v120
	ds_write_b32 v155, v121
	v_pk_add_f32 v[110:111], v[110:111], 1.0 op_sel_hi:[1,0]
	v_pk_fma_f32 v[118:119], v[114:115], v[114:115], 1.0 op_sel_hi:[1,1,0] neg_lo:[1,0,0] neg_hi:[1,0,0]
	v_rcp_f32_e32 v110, v110
	v_rcp_f32_e32 v111, v111
	v_sqrt_f32_e32 v118, v118
	v_sqrt_f32_e32 v119, v119
	ds_read2st64_b32 v[120:121], v139 offset0:164 offset1:166
	v_pk_fma_f32 v[116:117], v[116:117], s[4:5], v[90:91] op_sel_hi:[1,0,1] neg_lo:[1,0,0] neg_hi:[1,0,0]
	ds_write_b32 v156, v114
	v_exp_f32_e32 v116, v116
	v_exp_f32_e32 v117, v117
	v_pk_mul_f32 v[110:111], v[110:111], v[118:119]
	v_pk_fma_f32 v[112:113], v[112:113], s[4:5], v[128:129] op_sel_hi:[1,0,1] neg_lo:[1,0,0] neg_hi:[1,0,0]
	s_waitcnt lgkmcnt(1)
	v_pk_mul_f32 v[110:111], v[110:111], v[120:121]
	ds_write_b32 v157, v115
	ds_write_b32 v158, v110
	ds_write_b32 v159, v111
	v_pk_add_f32 v[110:111], v[116:117], 1.0 op_sel_hi:[1,0]
	v_exp_f32_e32 v112, v112
	v_rcp_f32_e32 v110, v110
	v_rcp_f32_e32 v111, v111
	v_exp_f32_e32 v113, v113
	ds_read2st64_b32 v[116:117], v139 offset0:168 offset1:170
	v_pk_mul_f32 v[110:111], v[130:131], v[110:111]
	s_nop 0
	v_exp_f32_e32 v110, v110
	v_exp_f32_e32 v111, v111
	v_pk_add_f32 v[112:113], v[112:113], 1.0 op_sel_hi:[1,0]
	v_pk_fma_f32 v[114:115], v[110:111], v[110:111], 1.0 op_sel_hi:[1,1,0] neg_lo:[1,0,0] neg_hi:[1,0,0]
	v_rcp_f32_e32 v112, v112
	v_rcp_f32_e32 v113, v113
	v_sqrt_f32_e32 v114, v114
	v_sqrt_f32_e32 v115, v115
	s_nop 0
	v_pk_mul_f32 v[112:113], v[112:113], v[114:115]
	s_waitcnt lgkmcnt(0)
	v_pk_mul_f32 v[112:113], v[112:113], v[116:117]
	ds_write_b32 v160, v110
	ds_write_b32 v161, v111
	ds_write_b32 v162, v112
	ds_write_b32 v163, v113
	s_waitcnt lgkmcnt(0)
	s_barrier
	ds_read2st64_b32 v[110:111], v164 offset0:196 offset1:198
	ds_read2st64_b32 v[112:113], v164 offset0:200 offset1:202
	ds_read_b32 v88, v165
	ds_read_b32 v109, v166
	ds_read_b32 v114, v167
	ds_read_b32 v115, v168
	ds_read_b32 v116, v169
	ds_read_b32 v117, v170
	ds_read_b32 v118, v171
	ds_read_b32 v119, v172
	s_waitcnt lgkmcnt(7)
	v_fmac_f32_e32 v88, 0, v110
	s_waitcnt lgkmcnt(6)
	v_fmac_f32_e32 v109, v88, v111
	v_mul_f32_e32 v88, v110, v111
	ds_read2st64_b32 v[110:111], v164 offset0:204 offset1:206
	s_waitcnt lgkmcnt(6)
	v_fmac_f32_e32 v114, v109, v112
	v_mul_f32_e32 v88, v88, v112
	s_waitcnt lgkmcnt(5)
	v_fmac_f32_e32 v115, v114, v113
	v_mul_f32_e32 v88, v88, v113
	ds_read2st64_b32 v[112:113], v164 offset0:208 offset1:210
	s_waitcnt lgkmcnt(1)
	v_fmac_f32_e32 v116, v115, v110
	v_mul_f32_e32 v88, v88, v110
	v_fmac_f32_e32 v117, v116, v111
	v_mul_f32_e32 v88, v88, v111
	s_waitcnt lgkmcnt(0)
	v_fmac_f32_e32 v118, v117, v112
	v_mul_f32_e32 v88, v88, v112
	v_fmac_f32_e32 v119, v118, v113
	v_mul_f32_e32 v88, v88, v113
	ds_read2st64_b32 v[110:111], v164 offset0:212 offset1:214
	ds_read2st64_b32 v[112:113], v164 offset0:216 offset1:218
	ds_read_b32 v109, v173
	ds_read_b32 v114, v174
	ds_read_b32 v115, v175
	ds_read_b32 v116, v176
	ds_read_b32 v117, v177
	ds_read_b32 v118, v178
	ds_read_b32 v120, v179
	ds_read_b32 v121, v180
	s_waitcnt lgkmcnt(7)
	v_fmac_f32_e32 v109, v119, v110
	v_mul_f32_e32 v88, v88, v110
	s_waitcnt lgkmcnt(6)
	v_fmac_f32_e32 v114, v109, v111
	v_mul_f32_e32 v88, v88, v111
	ds_read2st64_b32 v[110:111], v164 offset0:220 offset1:222
	s_waitcnt lgkmcnt(6)
	v_fmac_f32_e32 v115, v114, v112
	v_mul_f32_e32 v88, v88, v112
	s_waitcnt lgkmcnt(5)
	v_fmac_f32_e32 v116, v115, v113
	v_mul_f32_e32 v88, v88, v113
	ds_read2st64_b32 v[112:113], v164 offset0:224 offset1:226
	s_waitcnt lgkmcnt(1)
	v_mul_f32_e32 v88, v88, v110
	v_fmac_f32_e32 v117, v116, v110
	v_mul_f32_e32 v88, v88, v111
	v_fmac_f32_e32 v118, v117, v111
	s_waitcnt lgkmcnt(0)
	v_mul_f32_e32 v88, v88, v112
	v_fmac_f32_e32 v120, v118, v112
	v_mul_f32_e32 v88, v88, v113
	v_fmac_f32_e32 v121, v120, v113
	ds_write_b32 v136, v88
	ds_write_b32 v137, v121
	s_waitcnt lgkmcnt(0)
	s_barrier
	s_and_saveexec_b64 s[0:1], vcc
	s_cbranch_execz .LBB0_282
	ds_read_b32 v88, v181
	ds_read_b32 v109, v182
	ds_read_b32 v110, v183
	ds_read_b32 v111, v184
	ds_read_b32 v112, v185
	ds_read_b32 v113, v186
	ds_read_b32 v114, v187
	ds_read_b32 v115, v189
	s_and_b32 s5, s2, 0x60
	s_add_i32 s5, s5, s87
	s_waitcnt lgkmcnt(6)
	v_fmac_f32_e32 v109, 0, v88
	s_waitcnt lgkmcnt(5)
	v_mul_f32_e32 v88, v88, v110
	s_and_b32 s6, s2, 0x80
	s_waitcnt lgkmcnt(3)
	v_mul_f32_e32 v88, v88, v112
	s_add_i32 s5, s5, s6
	v_fmac_f32_e32 v111, v109, v110
	s_waitcnt lgkmcnt(1)
	v_mul_f32_e32 v109, v88, v114
	v_lshl_or_b32 v88, s5, 10, v190
	v_fmac_f32_e32 v113, v111, v112
	v_lshlrev_b64 v[110:111], 2, v[88:89]
	s_waitcnt lgkmcnt(0)
	v_fmac_f32_e32 v115, v113, v114
	v_lshl_add_u64 v[112:113], s[80:81], 0, v[110:111]
	v_lshl_add_u64 v[110:111], s[82:83], 0, v[110:111]
	s_waitcnt vmcnt(0)
	global_store_dword v[112:113], v109, off sc0 sc1
	global_store_dword v[110:111], v115, off sc0 sc1
	s_or_b64 exec, exec, s[0:1]
	s_add_i32 s2, s2, 32
	s_addk_i32 s3, 0x800
	s_cmpk_lg_i32 s2, 0x100
	s_cbranch_scc0 .LBB0_303
	s_branch .Llru1_waited
.LBB0_303:
	s_barrier
	s_getreg_b32 s2, hwreg(HW_REG_XCC_ID, 0, 4)
	s_waitcnt vmcnt(0)
	s_barrier
	s_mov_b64 s[0:1], exec
	v_readlane_b32 s4, v255, 2
	v_readlane_b32 s5, v255, 3
	s_and_b64 s[4:5], s[0:1], s[4:5]
	s_mov_b64 exec, s[4:5]
	s_cbranch_execz .Ls3_arrived
	v_readlane_b32 s2, v255, 0
	s_add_u32 s4, s92, 0x3800
	s_addc_u32 s5, s93, 0
	s_and_b32 s2, s2, 7
	s_lshl_b32 s2, s2, 7
	v_mov_b32_e32 v0, s2
	v_mov_b32_e32 v1, 1
	global_atomic_add v0, v1, s[4:5]
